# in-proj unit order: XCD-7 chunk fully rotated in both unit lists (first-unit and in-loop decode) so every padded-row/padded-token tile runs on a workgroup with slack; plus previous stack
# speedup vs baseline: 1.0288x; 1.0009x over previous
.LBB0_74:
	s_lshl_b32 s8, s35, 3
	s_waitcnt lgkmcnt(0)
	v_cvt_f32_u32_e32 v2, s8
	s_add_i32 s9, s34, s41
	s_add_i32 s9, s9, 0xffffffe8
	s_cmp_ge_i32 s9, s41
	s_cselect_b32 vcc_lo, s41, 0
	s_sub_i32 s9, s9, vcc_lo
	s_cmp_eq_u32 s37, 7
	s_cselect_b32 s9, s9, s34
	s_cmp_eq_u32 s64, 0
	s_cselect_b32 s9, s9, s34
	s_add_i32 s9, s38, s9
	s_sub_i32 s37, 0, s8
	s_abs_i32 s35, s9
	v_rcp_iflag_f32_e32 v2, v2
	s_ashr_i32 s34, s9, 31
	v_mul_f32_e32 v2, 0x4f7ffffe, v2
	v_cvt_u32_f32_e32 v2, v2
	s_nop 0
	v_readfirstlane_b32 s38, v2
	s_mul_i32 s37, s37, s38
	s_mul_hi_u32 s37, s38, s37
	s_add_i32 s38, s38, s37
	s_mul_hi_u32 s37, s35, s38
	s_mul_i32 s38, s37, s8
	s_sub_i32 s35, s35, s38
	s_add_i32 s39, s37, 1
	s_sub_i32 s38, s35, s8
	s_cmp_ge_u32 s35, s8
	s_cselect_b32 s37, s39, s37
	s_cselect_b32 s35, s38, s35
	s_add_i32 s38, s37, 1
	s_cmp_ge_u32 s35, s8
	s_cselect_b32 s35, s38, s37
	s_xor_b32 s35, s35, s34
	s_sub_i32 s34, s35, s34
	s_lshl_b32 s35, s34, 3
	s_mul_i32 s34, s34, s8
	s_sub_i32 s8, s17, s35
	s_min_i32 s17, s8, 8
	s_sext_i32_i16 s8, s17
	v_cvt_f32_i32_e32 v2, s8
	s_sub_i32 s34, s9, s34
	s_sext_i32_i16 s9, s34
	v_cvt_f32_i32_e32 v3, s9
	v_rcp_iflag_f32_e32 v4, v2
	s_xor_b32 s8, s9, s8
	s_ashr_i32 s8, s8, 30
	s_or_b32 s37, s8, 1
	v_mul_f32_e32 v4, v3, v4
	v_trunc_f32_e32 v4, v4
	v_fma_f32 v3, -v4, v2, v3
	v_cvt_i32_f32_e32 v4, v4
	v_cmp_ge_f32_e64 s[8:9], |v3|, |v2|
	s_and_b64 s[8:9], s[8:9], exec
	s_cselect_b32 s8, s37, 0
	v_readfirstlane_b32 s9, v4
	s_add_i32 s8, s9, s8
	s_sext_i32_i16 s44, s8
	s_mul_i32 s8, s8, s17
	s_sub_i32 s8, s34, s8
	s_sext_i32_i16 s8, s8
	s_add_i32 s96, s35, s8

.LBB0_89:
	s_lshl_b32 s4, s7, 3
	v_cvt_f32_u32_e32 v1, s4
	s_sub_i32 s7, 0, s4
	s_ashr_i32 s5, s45, 3
	s_add_i32 s5, s46, s5
	s_sub_i32 s45, s5, s46
	s_cmp_eq_u32 s63, 1
	s_cselect_b32 s65, 9, 24
	s_sub_i32 s65, s66, s65
	s_add_i32 s45, s45, s65
	s_cmp_ge_i32 s45, s66
	s_cselect_b32 s65, s66, 0
	s_sub_i32 s45, s45, s65
	s_add_i32 s45, s45, s46
	s_cmp_eq_u32 s47, 7
	s_cselect_b32 s5, s45, s5
	v_rcp_iflag_f32_e32 v1, v1
	s_abs_i32 s46, s5
	s_ashr_i32 s45, s5, 31
	v_mul_f32_e32 v1, 0x4f7ffffe, v1
	v_cvt_u32_f32_e32 v1, v1
	s_nop 0
	v_readfirstlane_b32 s47, v1
	s_mul_i32 s7, s7, s47
	s_mul_hi_u32 s7, s47, s7
	s_add_i32 s47, s47, s7
	s_mul_hi_u32 s7, s46, s47
	s_mul_i32 s47, s7, s4
	s_sub_i32 s46, s46, s47
	s_add_i32 s65, s7, 1
	s_sub_i32 s47, s46, s4
	s_cmp_ge_u32 s46, s4
	s_cselect_b32 s7, s65, s7
	s_cselect_b32 s46, s47, s46
	s_add_i32 s47, s7, 1
	s_cmp_ge_u32 s46, s4
	s_cselect_b32 s7, s47, s7
	s_xor_b32 s7, s7, s45
	s_sub_i32 s7, s7, s45
	s_lshl_b32 s45, s7, 3
	s_sub_i32 s6, s6, s45
	s_min_i32 s6, s6, 8
	s_abs_i32 s46, s6
	v_cvt_f32_u32_e32 v1, s46
	s_sub_i32 s47, 0, s46
	s_mul_i32 s7, s7, s4
	s_sub_i32 s4, s5, s7
	v_rcp_iflag_f32_e32 v1, v1
	s_abs_i32 s5, s4
	s_xor_b32 s7, s4, s6
	s_ashr_i32 s7, s7, 31
	v_mul_f32_e32 v1, 0x4f7ffffe, v1
	v_cvt_u32_f32_e32 v1, v1
	s_nop 0
	v_readfirstlane_b32 s65, v1
	s_mul_i32 s47, s47, s65
	s_mul_hi_u32 s47, s65, s47
	s_add_i32 s65, s65, s47
	s_mul_hi_u32 s47, s5, s65
	s_mul_i32 s65, s47, s46
	s_sub_i32 s5, s5, s65
	s_add_i32 s66, s47, 1
	s_sub_i32 s65, s5, s46
	s_cmp_ge_u32 s5, s46
	s_cselect_b32 s47, s66, s47
	s_cselect_b32 s5, s65, s5
	s_add_i32 s65, s47, 1
	s_cmp_ge_u32 s5, s46
	s_cselect_b32 s5, s65, s47
	s_xor_b32 s5, s5, s7
	s_sub_i32 s94, s5, s7
	s_mul_i32 s5, s94, s6
	s_sub_i32 s4, s4, s5
	s_add_i32 s6, s4, s45
